# v111 + waves 4-7 drop back to s_setprio 0 at the start of each GEMM tile epilogue (priority raised only through the k-loop)
# speedup vs baseline: 1.0066x; 1.0066x over previous
.LBB0_148:
	s_setprio 0
	v_readfirstlane_b32 s99, v195
	s_mov_b64 s[100:101], exec
	s_cmp_lg_u32 s99, 0
	s_cbranch_scc1 .Lpfa_skip_ip
	s_mov_b64 exec, 1
	v_lshl_add_u64 v[248:249], v[16:17], 2, s[0:1]
	global_atomic_add v248, v[248:249], v229, off sc0
	s_mov_b64 exec, s[100:101]

.LBB0_955:
	s_setprio 0
	v_readfirstlane_b32 s99, v195
	s_mov_b64 s[100:101], exec
	s_cmp_lg_u32 s99, 0
	s_cbranch_scc1 .Lpfa_skip_op
	s_mov_b64 exec, 1
	v_lshl_add_u64 v[248:249], v[16:17], 2, s[10:11]
	global_atomic_add v248, v[248:249], v229, off sc0
	s_mov_b64 exec, s[100:101]
